# P1 row order remapped the same way: sweep k writes, for every XCD, the h rows that P2 consumes k-th
# baseline (speedup 1.0000x reference)
.LBB0_137:
	s_cmp_lt_i32 s82, 2
	s_cselect_b64 s[0:1], -1, 0
	s_add_u32 s24, s78, 0x17e00000
	s_addc_u32 s25, s79, 0
	s_and_b64 s[4:5], s[0:1], s[4:5]
	s_cmp_lt_i32 s80, 0xa000
	s_cselect_b64 s[0:1], -1, 0
	v_writelane_b32 v254, s0, 50
	v_lshlrev_b32_e32 v216, 2, v217
	v_lshlrev_b32_e32 v212, 4, v217
	v_writelane_b32 v254, s1, 51
	s_and_b64 s[0:1], s[4:5], s[0:1]
	s_andn2_b64 vcc, exec, s[0:1]
	v_lshlrev_b32_e32 v214, 3, v217
	v_mbcnt_lo_u32_b32 v211, -1, 0
	s_cbranch_vccnz .LBB0_146
	s_lshr_b32 s52, s80, 9
	s_mulk_i32 s52, 0x1400
	s_and_b32 s53, s80, 0x1ff
	s_add_i32 s52, s52, s53
	s_add_i32 s54, s52, 0x1400
	s_mov_b32 s53, 0
	s_movk_i32 s8, 0x200
	s_add_i32 s14, s52, 0x5000
	s_ashr_i32 s81, s80, 31
	s_ashr_i32 s9, s8, 31
	s_ashr_i32 s15, s14, 31
	v_mov_b32_e32 v33, 0
	v_readlane_b32 s36, v254, 12
	v_or_b32_e32 v4, 0x300, v216
	s_lshl_b64 s[10:11], s[52:53], 11
	s_lshl_b64 s[12:13], s[8:9], 11
	s_lshl_b64 s[0:1], s[14:15], 12
	v_mbcnt_hi_u32_b32 v47, -1, v211
	v_mov_b32_e32 v213, v33
	v_readlane_b32 s40, v254, 16
	v_readlane_b32 s41, v254, 17
	v_or_b32_e32 v0, 0x100, v216
	v_or_b32_e32 v2, 0x200, v216
	v_mov_b32_e32 v215, v33
	v_lshlrev_b32_e32 v32, 1, v4
	s_add_u32 s20, s16, s0
	v_and_b32_e32 v1, 64, v47
	s_mov_b32 s7, 0
	v_lshl_add_u64 v[34:35], s[40:41], 0, v[212:213]
	v_lshl_add_u64 v[36:37], s[24:25], 0, v[214:215]
	v_lshl_add_u64 v[38:39], s[24:25], 0, v[32:33]
	v_lshl_add_u64 v[40:41], s[78:79], 0, v[214:215]
	s_addc_u32 s21, s17, s1
	s_lshl_b64 s[22:23], s[8:9], 12
	v_mov_b32_e32 v44, 0x358637bd
	s_mov_b32 s3, 0xf800000
	v_mov_b32_e32 v45, 0x260
	s_mov_b32 s35, 0x17e00000
	v_lshlrev_b32_e32 v32, 2, v4
	v_lshlrev_b32_e32 v46, 2, v216
	v_add_u32_e32 v48, 64, v1
	v_xor_b32_e32 v49, 1, v47
	v_xor_b32_e32 v50, 2, v47
	v_xor_b32_e32 v51, 4, v47
	v_xor_b32_e32 v52, 8, v47
	v_xor_b32_e32 v53, 16, v47
	v_xor_b32_e32 v54, 32, v47
	v_lshlrev_b32_e32 v55, 2, v0
	v_lshlrev_b32_e32 v56, 2, v2
	s_mov_b64 s[26:27], s[52:53]
	v_readlane_b32 s37, v254, 13
	v_readlane_b32 s38, v254, 14
	v_readlane_b32 s39, v254, 15
	v_readlane_b32 s42, v254, 18
	v_readlane_b32 s43, v254, 19
	v_readlane_b32 s44, v254, 20
	v_readlane_b32 s45, v254, 21
	v_readlane_b32 s46, v254, 22
	v_readlane_b32 s47, v254, 23
	v_readlane_b32 s48, v254, 24
	v_readlane_b32 s49, v254, 25
	v_readlane_b32 s50, v254, 26
	v_readlane_b32 s51, v254, 27
	s_branch .LBB0_141

.LBB0_140:
	v_lshl_add_u64 v[4:5], s[28:29], 0, v[32:33]
	v_add_co_u32_e32 v4, vcc, 0x1000, v4
	s_add_u32 s26, s26, s8
	s_nop 0
	v_addc_co_u32_e32 v5, vcc, 0, v5, vcc
	global_load_dwordx4 v[4:7], v[4:5], off
	s_nop 0
	global_load_dwordx4 v[8:11], v46, s[28:29] offset:3072
	s_addc_u32 s27, s27, s9
	s_add_u32 s10, s10, s12
	s_addc_u32 s11, s11, s13
	s_add_u32 s14, s14, s8
	s_addc_u32 s15, s15, s9
	s_add_u32 s20, s20, s22
	s_addc_u32 s21, s21, s23
	v_lshl_add_u64 v[12:13], v[38:39], 0, s[30:31]
	s_cmp_lt_i32 s26, s54
	s_waitcnt vmcnt(1)
	v_pk_add_f32 v[6:7], v[6:7], 1.0 op_sel_hi:[1,0]
	v_pk_add_f32 v[4:5], v[4:5], 1.0 op_sel_hi:[1,0]
	s_waitcnt vmcnt(0)
	v_pk_fma_f32 v[2:3], v[2:3], v[6:7], v[10:11]
	v_pk_fma_f32 v[0:1], v[0:1], v[4:5], v[8:9]
	s_nop 0
	v_cvt_pk_bf16_f32 v0, v0, v1
	v_cvt_pk_bf16_f32 v1, v2, v3
	global_store_dwordx2 v[12:13], v[0:1], off
	s_cbranch_scc0 .LBB0_146
.LBB0_141:
	s_add_i32 s0, s26, 0xffffe000
	s_add_u32 s46, s26, 0x5000
	s_lshr_b32 s1, s0, 12
	s_cmpk_lt_i32 s26, 0x2000
	s_cselect_b32 s6, 8, s1
	s_cselect_b32 s1, s27, 0
	s_cselect_b32 s0, s26, s0
	s_cselect_b32 s28, s17, s19
	s_cselect_b32 s29, s16, s18
	s_lshl_b64 s[0:1], s[0:1], 12
	s_add_u32 s42, s29, s0
	s_addc_u32 s43, s28, s1
	s_mov_b64 s[0:1], -1
	s_cmp_gt_i32 s46, 0x9fff
	s_mulk_i32 s6, 0x1800
	v_lshl_add_u64 v[42:43], v[40:41], 0, s[10:11]
	s_cbranch_scc0 .LBB0_143
	global_load_dwordx4 v[4:7], v46, s[42:43]
	global_load_dwordx4 v[8:11], v46, s[42:43] offset:1024
	global_load_dwordx4 v[0:3], v46, s[42:43] offset:3072
	global_load_dwordx4 v[12:15], v46, s[42:43] offset:2048
	s_lshl_b64 s[0:1], s[6:7], 2
	s_add_u32 s28, s78, s0
	s_addc_u32 s29, s79, s1
	s_add_u32 s30, s28, 0x1000
	s_addc_u32 s31, s29, 0
	v_cmp_lt_i32_e32 vcc, v49, v48
	global_load_dwordx4 v[16:19], v46, s[30:31]
	global_load_dwordx4 v[20:23], v[34:35], off
	v_cndmask_b32_e32 v24, v47, v49, vcc
	v_lshlrev_b32_e32 v57, 2, v24
	global_load_dwordx4 v[24:27], v46, s[28:29]
	v_cmp_lt_i32_e32 vcc, v50, v48
	s_waitcnt vmcnt(6)
	v_pk_mul_f32 v[28:29], v[6:7], v[6:7]
	v_pk_mul_f32 v[30:31], v[4:5], v[4:5]
	s_waitcnt vmcnt(5)
	v_pk_mul_f32 v[58:59], v[10:11], v[10:11]
	v_pk_mul_f32 v[60:61], v[8:9], v[8:9]
	v_pk_mov_b32 v[66:67], v[30:31], v[28:29] op_sel:[1,0]
	v_mov_b32_e32 v31, v29
	v_pk_mov_b32 v[28:29], v[60:61], v[58:59] op_sel:[1,0]
	v_mov_b32_e32 v61, v59
	s_waitcnt vmcnt(4)
	v_mul_f32_e32 v65, v0, v0
	s_waitcnt vmcnt(3)
	v_mul_f32_e32 v62, v13, v13
	v_mul_f32_e32 v64, v15, v15
	v_pk_add_f32 v[30:31], v[66:67], v[30:31]
	v_pk_add_f32 v[28:29], v[28:29], v[60:61]
	v_mul_f32_e32 v68, v1, v1
	v_mul_f32_e32 v69, v2, v2
	v_mul_f32_e32 v70, v3, v3
	v_pk_fma_f32 v[58:59], v[12:13], v[12:13], v[62:63] op_sel_hi:[1,1,0]
	v_pk_fma_f32 v[62:63], v[14:15], v[14:15], v[64:65] op_sel_hi:[1,1,0]
	v_pk_add_f32 v[30:31], v[30:31], v[30:31] op_sel:[0,1] op_sel_hi:[1,0]
	v_pk_add_f32 v[28:29], v[28:29], v[28:29] op_sel:[0,1] op_sel_hi:[1,0]
	v_mov_b32_e32 v59, v69
	v_mov_b32_e32 v63, v70
	v_mov_b32_e32 v31, v65
	v_mov_b32_e32 v29, v68
	v_pk_add_f32 v[58:59], v[58:59], v[62:63]
	v_pk_add_f32 v[28:29], v[30:31], v[28:29]
	v_cndmask_b32_e32 v30, v47, v50, vcc
	v_pk_add_f32 v[28:29], v[28:29], v[58:59]
	v_lshlrev_b32_e32 v30, 2, v30
	v_add_f32_e32 v28, v28, v29
	ds_bpermute_b32 v29, v57, v28
	v_cmp_lt_i32_e32 vcc, v51, v48
	s_waitcnt vmcnt(2)
	v_pk_add_f32 v[18:19], v[18:19], 1.0 op_sel_hi:[1,0]
	v_pk_add_f32 v[16:17], v[16:17], 1.0 op_sel_hi:[1,0]
	s_waitcnt lgkmcnt(0)
	v_add_f32_e32 v28, v28, v29
	ds_bpermute_b32 v29, v30, v28
	v_cndmask_b32_e32 v30, v47, v51, vcc
	v_lshlrev_b32_e32 v30, 2, v30
	v_cmp_lt_i32_e32 vcc, v52, v48
	s_waitcnt lgkmcnt(0)
	v_add_f32_e32 v28, v28, v29
	ds_bpermute_b32 v29, v30, v28
	v_cndmask_b32_e32 v30, v47, v52, vcc
	v_lshlrev_b32_e32 v30, 2, v30
	v_cmp_lt_i32_e32 vcc, v53, v48
	s_waitcnt lgkmcnt(0)
	v_add_f32_e32 v28, v28, v29
	ds_bpermute_b32 v29, v30, v28
	v_cndmask_b32_e32 v30, v47, v53, vcc
	v_lshlrev_b32_e32 v30, 2, v30
	v_cmp_lt_i32_e32 vcc, v54, v48
	s_waitcnt lgkmcnt(0)
	v_add_f32_e32 v28, v28, v29
	ds_bpermute_b32 v29, v30, v28
	v_cndmask_b32_e32 v30, v47, v54, vcc
	v_lshlrev_b32_e32 v30, 2, v30
	s_waitcnt lgkmcnt(0)
	v_add_f32_e32 v28, v28, v29
	ds_bpermute_b32 v29, v30, v28
	s_waitcnt lgkmcnt(0)
	v_add_f32_e32 v28, v28, v29
	v_fmamk_f32 v28, v28, 0x3a800000, v44
	v_mul_f32_e32 v29, 0x4f800000, v28
	v_cmp_gt_f32_e32 vcc, s3, v28
	s_nop 1
	v_cndmask_b32_e32 v30, v28, v29, vcc
	v_sqrt_f32_e32 v31, v30
	v_add_co_u32_e64 v28, s[0:1], s35, v42
	v_add_u32_e32 v57, -1, v31
	s_nop 0
	v_addc_co_u32_e64 v29, s[0:1], 0, v43, s[0:1]
	v_add_u32_e32 v58, 1, v31
	v_fma_f32 v59, -v57, v31, v30
	v_fma_f32 v60, -v58, v31, v30
	v_cmp_ge_f32_e64 s[0:1], 0, v59
	s_nop 1
	v_cndmask_b32_e64 v31, v31, v57, s[0:1]
	v_cmp_lt_f32_e64 s[0:1], 0, v60
	s_nop 1
	v_cndmask_b32_e64 v31, v31, v58, s[0:1]
	v_mul_f32_e32 v57, 0x37800000, v31
	v_cndmask_b32_e32 v31, v31, v57, vcc
	v_cmp_class_f32_e32 vcc, v30, v45
	s_nop 1
	v_cndmask_b32_e32 v30, v31, v30, vcc
	v_div_scale_f32 v31, s[0:1], v30, v30, 1.0
	v_rcp_f32_e32 v57, v31
	v_div_scale_f32 v58, vcc, 1.0, v30, 1.0
	s_mov_b64 s[0:1], 0
	v_fma_f32 v59, -v31, v57, 1.0
	v_fmac_f32_e32 v57, v59, v57
	v_mul_f32_e32 v59, v58, v57
	v_fma_f32 v60, -v31, v59, v58
	v_fmac_f32_e32 v59, v60, v57
	v_fma_f32 v31, -v31, v59, v58
	v_div_fmas_f32 v31, v31, v57, v59
	v_div_fixup_f32 v30, v31, v30, 1.0
	v_pk_mul_f32 v[6:7], v[6:7], v[30:31] op_sel_hi:[1,0]
	v_pk_mul_f32 v[4:5], v[4:5], v[30:31] op_sel_hi:[1,0]
	s_waitcnt vmcnt(1)
	v_pk_mul_f32 v[6:7], v[22:23], v[6:7]
	v_pk_mul_f32 v[4:5], v[20:21], v[4:5]
	s_waitcnt vmcnt(0)
	v_pk_fma_f32 v[6:7], v[18:19], v[6:7], v[26:27]
	v_pk_fma_f32 v[4:5], v[16:17], v[4:5], v[24:25]
	v_pk_mul_f32 v[10:11], v[10:11], v[30:31] op_sel_hi:[1,0]
	v_cvt_pk_bf16_f32 v4, v4, v5
	v_cvt_pk_bf16_f32 v5, v6, v7
	global_store_dwordx2 v[28:29], v[4:5], off
	global_load_dwordx4 v[4:7], v[34:35], off offset:1024
	s_nop 0
	global_load_dwordx4 v[16:19], v55, s[30:31]
	global_load_dwordx4 v[20:23], v46, s[28:29] offset:1024
	v_pk_mul_f32 v[8:9], v[8:9], v[30:31] op_sel_hi:[1,0]
	v_pk_mul_f32 v[14:15], v[14:15], v[30:31] op_sel_hi:[1,0]
	v_pk_mul_f32 v[12:13], v[12:13], v[30:31] op_sel_hi:[1,0]
	v_pk_mul_f32 v[2:3], v[2:3], v[30:31] op_sel_hi:[1,0]
	v_pk_mul_f32 v[0:1], v[0:1], v[30:31] op_sel_hi:[1,0]
	s_waitcnt vmcnt(2)
	v_pk_mul_f32 v[4:5], v[4:5], v[8:9]
	v_pk_mul_f32 v[6:7], v[6:7], v[10:11]
	s_waitcnt vmcnt(1)
	v_pk_add_f32 v[8:9], v[18:19], 1.0 op_sel_hi:[1,0]
	v_pk_add_f32 v[10:11], v[16:17], 1.0 op_sel_hi:[1,0]
	s_waitcnt vmcnt(0)
	v_pk_fma_f32 v[6:7], v[8:9], v[6:7], v[22:23]
	v_pk_fma_f32 v[4:5], v[10:11], v[4:5], v[20:21]
	s_nop 0
	v_cvt_pk_bf16_f32 v4, v4, v5
	v_cvt_pk_bf16_f32 v5, v6, v7
	global_store_dwordx2 v[28:29], v[4:5], off offset:512
	global_load_dwordx4 v[4:7], v[34:35], off offset:2048
	s_nop 0
	global_load_dwordx4 v[8:11], v56, s[30:31]
	global_load_dwordx4 v[16:19], v46, s[28:29] offset:2048
	s_waitcnt vmcnt(2)
	v_pk_mul_f32 v[4:5], v[4:5], v[12:13]
	v_pk_mul_f32 v[6:7], v[6:7], v[14:15]
	s_waitcnt vmcnt(1)
	v_pk_add_f32 v[10:11], v[10:11], 1.0 op_sel_hi:[1,0]
	v_pk_add_f32 v[8:9], v[8:9], 1.0 op_sel_hi:[1,0]
	s_waitcnt vmcnt(0)
	v_pk_fma_f32 v[6:7], v[6:7], v[10:11], v[18:19]
	v_pk_fma_f32 v[4:5], v[4:5], v[8:9], v[16:17]
	s_nop 0
	v_cvt_pk_bf16_f32 v4, v4, v5
	v_cvt_pk_bf16_f32 v5, v6, v7
	global_store_dwordx2 v[28:29], v[4:5], off offset:1024
	global_load_dwordx4 v[4:7], v[34:35], off offset:3072
	s_waitcnt vmcnt(0)
	v_pk_mul_f32 v[0:1], v[0:1], v[4:5]
	v_pk_mul_f32 v[2:3], v[2:3], v[6:7]
